# final norm: xs row loads default policy instead of nt; on v91
# speedup vs baseline: 1.0035x; 1.0035x over previous
; template <class T> __device__ __forceinline__ T* launder(T* p) { asm volatile("" : "+s"(p)); return p; }
; #define GAS __attribute__((address_space(1)))
; __device__ __forceinline__ float sumsq8(const u32x4 w) { const f32x4 a = unpack_lo4(w), b = unpack_hi4(w); return ((a.x * a.x + a.y * a.y) + (a.z * a.z + a.w * a.w)) + ((b.x * b.x + b.y * b.y) + (b.z * b.z + b.w * b.w)); }
; #define KARG(f) (kargp[opaque_zero()].f)
; #define FRESH_LANE() fresh_lane()
; template <int R> __device__ __forceinline__ void final_norm_rows_bf16in(const bf16* x, float* o, int m0, int rstride, const float* g, int lane) {
;     u32x4 v[R][2]; float s[R];
; #pragma unroll
;     for (int r = 0; r < R; ++r) { const GAS u32x4* xr = (const GAS u32x4*)(x + (size_t)(m0 + r * rstride) * D) + lane; v[r][0] = __builtin_nontemporal_load(xr); v[r][1] = __builtin_nontemporal_load(xr + 64); }
; #pragma unroll
;     for (int r = 0; r < R; ++r) { s[r] = 0.f;
; #pragma unroll
;         for (int j = 0; j < 2; ++j) s[r] += sumsq8(v[r][j]); }
; __global__ void __launch_bounds__(NWAVES * 64, 2) fwd_megakernel(Args a_unused) {
;     ...
;     { float* outp = launder(KARG(out)); const bf16* xs = (const bf16*)(launder(ws) + WS_XS); const int ln = FRESH_LANE(); for (int it = 0, m = gw; it < M / (4 * NGW); ++it, m += 4 * NGW) final_norm_rows_bf16in<4>(xs, outp, m, NGW, KARG(g_final), ln); }
.LBB0_788:
	s_mov_b32 s2, 0
	s_mul_hi_i32 s3, s2, 0xc8
	s_mulk_i32 s2, 0xc8
	s_add_u32 s2, s0, s2
	v_cmp_lt_i32_e32 vcc, v214, v213
	s_addc_u32 s3, s1, s3
	s_add_u32 s4, s20, s16
	v_cndmask_b32_e32 v0, v212, v214, vcc
	v_cmp_lt_i32_e32 vcc, v215, v213
	s_load_dwordx2 s[2:3], s[2:3], 0x90
	s_addc_u32 s5, s21, s17
	v_cndmask_b32_e32 v1, v212, v215, vcc
	s_add_i32 s6, s12, 0xfffff800
	v_cmp_lt_i32_e32 vcc, v216, v213
	v_lshlrev_b32_e32 v128, 2, v0
	v_lshlrev_b32_e32 v129, 2, v1
	v_lshl_add_u64 v[0:1], s[4:5], 0, v[32:33]
	s_ashr_i32 s7, s6, 31
	v_cndmask_b32_e32 v2, v212, v216, vcc
	v_cmp_lt_i32_e32 vcc, v217, v213
	global_load_dwordx4 v[50:53], v[0:1], off offset:1024
	global_load_dwordx4 v[60:63], v[0:1], off
	s_lshl_b64 s[4:5], s[6:7], 11
	v_cndmask_b32_e32 v3, v212, v217, vcc
	v_cmp_lt_i32_e32 vcc, v218, v213
	s_add_u32 s4, s18, s4
	s_addc_u32 s5, s19, s5
	v_cndmask_b32_e32 v4, v212, v218, vcc
	v_cmp_lt_i32_e32 vcc, v219, v213
	s_ashr_i32 s13, s12, 31
	s_waitcnt lgkmcnt(0)
	v_lshl_add_u64 v[40:41], s[2:3], 0, v[34:35]
	v_cndmask_b32_e32 v5, v212, v219, vcc
	s_lshl_b64 s[2:3], s[12:13], 11
	v_lshlrev_b32_e32 v130, 2, v2
	v_lshlrev_b32_e32 v131, 2, v3
	v_lshlrev_b32_e32 v132, 2, v4
	v_lshlrev_b32_e32 v133, 2, v5
	v_lshl_add_u64 v[8:9], s[4:5], 0, v[32:33]
	global_load_dwordx4 v[0:3], v[40:41], off offset:16
	global_load_dwordx4 v[4:7], v[40:41], off
	global_load_dwordx4 v[20:23], v[8:9], off offset:1024
	global_load_dwordx4 v[16:19], v[8:9], off
	s_add_u32 s4, s18, s2
	s_addc_u32 s5, s19, s3
	s_add_i32 s2, s12, 0x800
	v_lshl_add_u64 v[24:25], s[4:5], 0, v[32:33]
	s_ashr_i32 s3, s2, 31
	global_load_dwordx4 v[8:11], v[24:25], off
	global_load_dwordx4 v[12:15], v[24:25], off offset:1024
	s_lshl_b64 s[4:5], s[2:3], 11
	s_add_u32 s4, s18, s4
	s_addc_u32 s5, s19, s5
	v_lshl_add_u64 v[38:39], s[4:5], 0, v[32:33]
	global_load_dwordx4 v[24:27], v[38:39], off
	global_load_dwordx4 v[28:31], v[38:39], off offset:1024
	s_lshl_b64 s[6:7], s[6:7], 12
	s_add_u32 s4, s10, s6
	s_addc_u32 s5, s11, s7
	s_lshl_b64 s[6:7], s[12:13], 12
	v_lshl_add_u64 v[38:39], s[4:5], 0, v[34:35]
	s_add_u32 s4, s10, s6
	s_addc_u32 s5, s11, s7
	s_lshl_b64 s[2:3], s[2:3], 12
	s_add_u32 s2, s10, s2
	s_addc_u32 s3, s11, s3
	v_lshl_add_u64 v[44:45], s[2:3], 0, v[34:35]
	v_lshl_add_u64 v[42:43], s[4:5], 0, v[34:35]
	v_lshl_add_u64 v[36:37], s[14:15], 0, v[34:35]
	s_add_u32 s14, s14, 0x2000000
	s_addc_u32 s15, s15, 0
	s_add_u32 s16, s16, 0x1000000
	s_addc_u32 s17, s17, 0
	s_addk_i32 s12, 0x2000
	s_cmp_eq_u32 s16, 0x8000000
	s_waitcnt vmcnt(0)
	v_lshlrev_b32_e32 v55, 16, v50
	v_and_b32_e32 v47, 0xffff0000, v50
	v_and_b32_e32 v46, 0xffff0000, v60
	v_lshlrev_b32_e32 v57, 16, v51
	v_lshlrev_b32_e32 v56, 16, v61
	v_and_b32_e32 v49, 0xffff0000, v51
	v_and_b32_e32 v48, 0xffff0000, v61
	v_lshlrev_b32_e32 v59, 16, v52
	v_and_b32_e32 v51, 0xffff0000, v52
	v_and_b32_e32 v50, 0xffff0000, v62
	v_lshlrev_b32_e32 v61, 16, v53
	v_and_b32_e32 v53, 0xffff0000, v53
	v_and_b32_e32 v52, 0xffff0000, v63
	v_lshlrev_b32_e32 v54, 16, v60
	v_lshlrev_b32_e32 v58, 16, v62
	v_lshlrev_b32_e32 v60, 16, v63
	v_pk_mul_f32 v[62:63], v[46:47], v[46:47]
	v_pk_mul_f32 v[64:65], v[48:49], v[48:49]
	v_pk_mul_f32 v[66:67], v[50:51], v[50:51]
	v_pk_mul_f32 v[68:69], v[52:53], v[52:53]
	v_pk_fma_f32 v[62:63], v[54:55], v[54:55], v[62:63]
	v_pk_fma_f32 v[64:65], v[56:57], v[56:57], v[64:65]
	v_pk_fma_f32 v[66:67], v[58:59], v[58:59], v[66:67]
	v_pk_fma_f32 v[68:69], v[60:61], v[60:61], v[68:69]
	v_pk_add_f32 v[62:63], v[62:63], v[64:65]
	v_pk_add_f32 v[64:65], v[66:67], v[68:69]
	v_lshlrev_b32_e32 v67, 16, v21
	v_pk_add_f32 v[72:73], v[62:63], v[64:65]
	v_lshlrev_b32_e32 v65, 16, v20
	v_lshlrev_b32_e32 v64, 16, v16
	v_and_b32_e32 v63, 0xffff0000, v20
	v_and_b32_e32 v62, 0xffff0000, v16
	v_lshlrev_b32_e32 v66, 16, v17
	v_and_b32_e32 v21, 0xffff0000, v21
	v_and_b32_e32 v20, 0xffff0000, v17
	v_lshlrev_b32_e32 v69, 16, v22
	v_and_b32_e32 v17, 0xffff0000, v22
	v_and_b32_e32 v16, 0xffff0000, v18
	v_lshlrev_b32_e32 v71, 16, v23
	v_and_b32_e32 v23, 0xffff0000, v23
	v_and_b32_e32 v22, 0xffff0000, v19
	v_mov_b32_e32 v89, v46
	v_lshlrev_b32_e32 v68, 16, v18
	v_lshlrev_b32_e32 v70, 16, v19
	v_add_f32_e32 v46, v72, v73
	v_pk_mul_f32 v[18:19], v[62:63], v[62:63]
	v_pk_mul_f32 v[72:73], v[20:21], v[20:21]
	v_pk_mul_f32 v[74:75], v[16:17], v[16:17]
	v_pk_mul_f32 v[76:77], v[22:23], v[22:23]
	v_mov_b32_e32 v101, v16
	v_pk_fma_f32 v[18:19], v[64:65], v[64:65], v[18:19]
	v_pk_fma_f32 v[72:73], v[66:67], v[66:67], v[72:73]
	v_pk_fma_f32 v[74:75], v[68:69], v[68:69], v[74:75]
	v_pk_fma_f32 v[76:77], v[70:71], v[70:71], v[76:77]
	ds_bpermute_b32 v16, v128, v46
	v_pk_add_f32 v[80:81], v[18:19], v[72:73]
	v_pk_add_f32 v[82:83], v[74:75], v[76:77]
	v_lshlrev_b32_e32 v73, 16, v12
	v_lshlrev_b32_e32 v72, 16, v8
	v_and_b32_e32 v19, 0xffff0000, v12
	v_and_b32_e32 v18, 0xffff0000, v8
	v_lshlrev_b32_e32 v75, 16, v13
	v_lshlrev_b32_e32 v74, 16, v9
	v_and_b32_e32 v13, 0xffff0000, v13
	v_and_b32_e32 v12, 0xffff0000, v9
	v_lshlrev_b32_e32 v77, 16, v14
	v_and_b32_e32 v9, 0xffff0000, v14
	v_and_b32_e32 v8, 0xffff0000, v10
	v_lshlrev_b32_e32 v79, 16, v15
	v_and_b32_e32 v15, 0xffff0000, v15
	v_and_b32_e32 v14, 0xffff0000, v11
	v_lshlrev_b32_e32 v76, 16, v10
	v_lshlrev_b32_e32 v78, 16, v11
	v_pk_add_f32 v[10:11], v[80:81], v[82:83]
	v_pk_mul_f32 v[80:81], v[18:19], v[18:19]
	v_pk_mul_f32 v[82:83], v[12:13], v[12:13]
	v_pk_mul_f32 v[84:85], v[8:9], v[8:9]
	v_pk_mul_f32 v[86:87], v[14:15], v[14:15]
	v_mov_b32_e32 v111, v8
	v_add_f32_e32 v8, v10, v11
	v_pk_fma_f32 v[10:11], v[72:73], v[72:73], v[80:81]
	v_pk_fma_f32 v[80:81], v[74:75], v[74:75], v[82:83]
	v_pk_fma_f32 v[82:83], v[76:77], v[76:77], v[84:85]
	v_pk_fma_f32 v[84:85], v[78:79], v[78:79], v[86:87]
	v_pk_add_f32 v[10:11], v[10:11], v[80:81]
	v_pk_add_f32 v[80:81], v[82:83], v[84:85]
	v_mov_b32_e32 v109, v12
	v_mov_b32_e32 v113, v14
	ds_bpermute_b32 v12, v128, v8
	v_pk_add_f32 v[114:115], v[10:11], v[80:81]
	s_waitcnt lgkmcnt(1)
; #define GAS __attribute__((address_space(1)))
; __device__ __forceinline__ float sumsq8(const u32x4 w) { const f32x4 a = unpack_lo4(w), b = unpack_hi4(w); return ((a.x * a.x + a.y * a.y) + (a.z * a.z + a.w * a.w)) + ((b.x * b.x + b.y * b.y) + (b.z * b.z + b.w * b.w)); }
; template <int R> __device__ __forceinline__ void final_norm_rows_bf16in(const bf16* x, float* o, int m0, int rstride, const float* g, int lane) {
;     ...
;     for (int r = 0; r < R; ++r) { s[r] = 0.f;
; #pragma unroll
;         for (int j = 0; j < 2; ++j) s[r] += sumsq8(v[r][j]); }
; #pragma unroll
;     for (int of = 1; of < 64; of <<= 1) {
; #pragma unroll
;         for (int r = 0; r < R; ++r) s[r] += __shfl_xor(s[r], of); }
; #pragma unroll
;     for (int j = 0; j < 2; ++j) {
;         const int i4 = 2 * (lane + 64 * j);
;         const f32x4 g0 = ((const GAS f32x4*)g)[i4], g1 = ((const GAS f32x4*)g)[i4 + 1];
; #pragma unroll
;         for (int r = 0; r < R; ++r) {
;             const float rstd = 1.0f / sqrtf(s[r] * (1.0f / D) + EPS);
	v_add_f32_e32 v14, v46, v16
	v_mov_b32_e32 v107, v18
	v_and_b32_e32 v11, 0xffff0000, v28
	v_and_b32_e32 v10, 0xffff0000, v24
	v_add_f32_e32 v16, v114, v115
	ds_bpermute_b32 v18, v129, v14
	v_lshlrev_b32_e32 v81, 16, v28
	v_lshlrev_b32_e32 v80, 16, v24
	v_lshlrev_b32_e32 v83, 16, v29
	v_lshlrev_b32_e32 v82, 16, v25
	v_and_b32_e32 v29, 0xffff0000, v29
	v_and_b32_e32 v28, 0xffff0000, v25
	v_lshlrev_b32_e32 v85, 16, v30
	v_lshlrev_b32_e32 v84, 16, v26
	v_and_b32_e32 v25, 0xffff0000, v30
	v_and_b32_e32 v24, 0xffff0000, v26
	v_lshlrev_b32_e32 v87, 16, v31
	v_lshlrev_b32_e32 v86, 16, v27
	v_and_b32_e32 v31, 0xffff0000, v31
	v_and_b32_e32 v30, 0xffff0000, v27
	v_pk_mul_f32 v[26:27], v[10:11], v[10:11]
	v_mov_b32_e32 v121, v10
	ds_bpermute_b32 v10, v128, v16
	v_pk_mul_f32 v[114:115], v[28:29], v[28:29]
	v_pk_mul_f32 v[116:117], v[24:25], v[24:25]
	v_pk_mul_f32 v[118:119], v[30:31], v[30:31]
	v_pk_fma_f32 v[26:27], v[80:81], v[80:81], v[26:27]
	v_pk_fma_f32 v[114:115], v[82:83], v[82:83], v[114:115]
	v_pk_fma_f32 v[116:117], v[84:85], v[84:85], v[116:117]
	v_pk_fma_f32 v[118:119], v[86:87], v[86:87], v[118:119]
	v_pk_add_f32 v[26:27], v[26:27], v[114:115]
	v_pk_add_f32 v[114:115], v[116:117], v[118:119]
	s_waitcnt lgkmcnt(2)
	v_add_f32_e32 v8, v8, v12
	v_mov_b32_e32 v99, v20
	v_pk_add_f32 v[26:27], v[26:27], v[114:115]
	ds_bpermute_b32 v20, v129, v8
	s_waitcnt lgkmcnt(2)
	v_add_f32_e32 v14, v14, v18
	v_add_f32_e32 v12, v26, v27
	s_waitcnt lgkmcnt(1)
	v_add_f32_e32 v10, v16, v10
	ds_bpermute_b32 v16, v130, v14
	v_mov_b32_e32 v103, v22
	ds_bpermute_b32 v22, v128, v12
	ds_bpermute_b32 v18, v129, v10
	s_waitcnt lgkmcnt(3)
	v_add_f32_e32 v8, v8, v20
	ds_bpermute_b32 v20, v130, v8
	s_waitcnt lgkmcnt(3)
	v_add_f32_e32 v14, v14, v16
	s_waitcnt lgkmcnt(2)
	v_add_f32_e32 v12, v12, v22
	ds_bpermute_b32 v16, v131, v14
	ds_bpermute_b32 v22, v129, v12
	s_waitcnt lgkmcnt(3)
	v_add_f32_e32 v10, v10, v18
	ds_bpermute_b32 v18, v130, v10
	s_waitcnt lgkmcnt(3)
	v_add_f32_e32 v8, v8, v20
	ds_bpermute_b32 v20, v131, v8
	s_waitcnt lgkmcnt(3)
	v_add_f32_e32 v14, v14, v16
	s_waitcnt lgkmcnt(2)
	v_add_f32_e32 v12, v12, v22
	ds_bpermute_b32 v16, v132, v14
	ds_bpermute_b32 v22, v130, v12
	s_waitcnt lgkmcnt(3)
	v_add_f32_e32 v10, v10, v18
	ds_bpermute_b32 v18, v131, v10
	s_waitcnt lgkmcnt(3)
	v_add_f32_e32 v8, v8, v20
	ds_bpermute_b32 v20, v132, v8
	s_waitcnt lgkmcnt(3)
	v_add_f32_e32 v14, v14, v16
	s_waitcnt lgkmcnt(2)
	v_add_f32_e32 v12, v12, v22
	ds_bpermute_b32 v16, v133, v14
	ds_bpermute_b32 v22, v131, v12
	s_waitcnt lgkmcnt(3)
	v_add_f32_e32 v10, v10, v18
	ds_bpermute_b32 v18, v132, v10
	s_waitcnt lgkmcnt(3)
	v_add_f32_e32 v8, v8, v20
	ds_bpermute_b32 v20, v133, v8
	s_waitcnt lgkmcnt(3)
	v_add_f32_e32 v14, v14, v16
	s_waitcnt lgkmcnt(2)
	v_add_f32_e32 v12, v12, v22
	v_fmamk_f32 v14, v14, 0x3a800000, v104
	ds_bpermute_b32 v22, v132, v12
	s_waitcnt lgkmcnt(2)
	v_add_f32_e32 v10, v10, v18
	v_mul_f32_e32 v18, 0x4f800000, v14
	v_cmp_gt_f32_e32 vcc, s22, v14
	ds_bpermute_b32 v16, v133, v10
	s_waitcnt lgkmcnt(2)
	v_add_f32_e32 v8, v8, v20
	v_cndmask_b32_e32 v14, v14, v18, vcc
	v_sqrt_f32_e32 v18, v14
	v_fmamk_f32 v8, v8, 0x3a800000, v104
	s_waitcnt lgkmcnt(1)
	v_add_f32_e32 v12, v12, v22
	v_mul_f32_e32 v22, 0x4f800000, v8
	v_cmp_gt_f32_e64 s[2:3], s22, v8
	ds_bpermute_b32 v20, v133, v12
	s_waitcnt lgkmcnt(1)
	v_add_f32_e32 v10, v10, v16
	v_cndmask_b32_e64 v8, v8, v22, s[2:3]
	v_add_u32_e32 v16, -1, v18
	v_mov_b32_e32 v125, v24
	v_add_u32_e32 v22, 1, v18
	v_sqrt_f32_e32 v24, v8
	v_fma_f32 v26, -v16, v18, v14
	v_fmamk_f32 v10, v10, 0x3a800000, v104
	v_fma_f32 v27, -v22, v18, v14
	v_cmp_ge_f32_e64 s[6:7], 0, v26
	v_mov_b32_e32 v123, v28
	v_mul_f32_e32 v28, 0x4f800000, v10
	v_cmp_gt_f32_e64 s[4:5], s22, v10
	v_cndmask_b32_e64 v16, v18, v16, s[6:7]
	v_cmp_lt_f32_e64 s[6:7], 0, v27
	v_cndmask_b32_e64 v10, v10, v28, s[4:5]
	s_waitcnt lgkmcnt(0)
	v_add_f32_e32 v12, v12, v20
	v_cndmask_b32_e64 v16, v16, v22, s[6:7]
	v_sqrt_f32_e32 v18, v10
	v_mul_f32_e32 v20, 0x37800000, v16
	v_add_u32_e32 v22, -1, v24
	v_add_u32_e32 v26, 1, v24
	v_cndmask_b32_e32 v16, v16, v20, vcc
	v_fma_f32 v20, -v22, v24, v8
	v_cmp_class_f32_e64 s[6:7], v14, v105
	v_fmamk_f32 v12, v12, 0x3a800000, v104
	v_fma_f32 v27, -v26, v24, v8
	v_cndmask_b32_e64 v14, v16, v14, s[6:7]
	v_cmp_ge_f32_e64 s[6:7], 0, v20
	v_mul_f32_e32 v28, 0x4f800000, v12
	v_cmp_gt_f32_e32 vcc, s22, v12
	v_cndmask_b32_e64 v16, v24, v22, s[6:7]
	v_cmp_lt_f32_e64 s[6:7], 0, v27
	v_cndmask_b32_e32 v12, v12, v28, vcc
	v_add_u32_e32 v24, -1, v18
	v_cndmask_b32_e64 v16, v16, v26, s[6:7]
	v_mov_b32_e32 v127, v30
	v_add_u32_e32 v26, 1, v18
	v_sqrt_f32_e32 v27, v12
	v_mul_f32_e32 v30, 0x37800000, v16
	v_fma_f32 v46, -v24, v18, v10
	v_mov_b32_e32 v91, v48
	v_div_scale_f32 v20, s[8:9], v14, v14, 1.0
	v_fma_f32 v48, -v26, v18, v10
	v_cndmask_b32_e64 v16, v16, v30, s[2:3]
	v_cmp_ge_f32_e64 s[2:3], 0, v46
	v_rcp_f32_e32 v28, v20
	v_cmp_class_f32_e64 s[6:7], v8, v105
	v_cndmask_b32_e64 v18, v18, v24, s[2:3]
	v_cmp_lt_f32_e64 s[2:3], 0, v48
	v_cndmask_b32_e64 v8, v16, v8, s[6:7]
	v_add_u32_e32 v30, -1, v27
	v_cndmask_b32_e64 v16, v18, v26, s[2:3]
	v_mul_f32_e32 v26, 0x37800000, v16
	v_div_scale_f32 v18, s[2:3], v8, v8, 1.0
	v_add_u32_e32 v46, 1, v27
	v_cndmask_b32_e64 v16, v16, v26, s[4:5]
	v_cmp_class_f32_e64 s[4:5], v10, v105
	v_fma_f32 v26, -v30, v27, v12
	v_mov_b32_e32 v93, v50
	v_mov_b32_e32 v95, v52
	v_fma_f32 v48, -v20, v28, 1.0
	v_rcp_f32_e32 v50, v18
	v_fma_f32 v52, -v46, v27, v12
	v_cndmask_b32_e64 v10, v16, v10, s[4:5]
	v_cmp_ge_f32_e64 s[4:5], 0, v26
	v_div_scale_f32 v22, s[8:9], 1.0, v14, 1.0
	v_fmac_f32_e32 v28, v48, v28
	v_cndmask_b32_e64 v16, v27, v30, s[4:5]
; #define GAS __attribute__((address_space(1)))
; __device__ __forceinline__ f32x4 unpack_lo4(const u32x4 w) { return (f32x4){bf_lo(w.x), bf_hi(w.x), bf_lo(w.y), bf_hi(w.y)}; }
; __device__ __forceinline__ f32x4 unpack_hi4(const u32x4 w) { return (f32x4){bf_lo(w.z), bf_hi(w.z), bf_lo(w.w), bf_hi(w.w)}; }
; template <int R> __device__ __forceinline__ void final_norm_rows_bf16in(const bf16* x, float* o, int m0, int rstride, const float* g, int lane) {
;     ...
;     for (int j = 0; j < 2; ++j) {
;         const int i4 = 2 * (lane + 64 * j);
;         const f32x4 g0 = ((const GAS f32x4*)g)[i4], g1 = ((const GAS f32x4*)g)[i4 + 1];
; #pragma unroll
;         for (int r = 0; r < R; ++r) {
;             const float rstd = 1.0f / sqrtf(s[r] * (1.0f / D) + EPS);
;             GAS f32x4* op = (GAS f32x4*)(o + (size_t)(m0 + r * rstride) * D) + i4;
;             __builtin_nontemporal_store(unpack_lo4(v[r][j]) * rstd * g0, op); __builtin_nontemporal_store(unpack_hi4(v[r][j]) * rstd * g1, op + 1);
;         }
;     }
	v_cmp_lt_f32_e64 s[4:5], 0, v52
	v_mul_f32_e32 v26, v22, v28
	v_div_scale_f32 v27, s[6:7], v10, v10, 1.0
	v_cndmask_b32_e64 v16, v16, v46, s[4:5]
	v_fma_f32 v46, -v20, v26, v22
	v_rcp_f32_e32 v48, v27
	v_mul_f32_e32 v52, 0x37800000, v16
	v_fmac_f32_e32 v26, v46, v28
	v_fma_f32 v46, -v18, v50, 1.0
	v_cndmask_b32_e32 v16, v16, v52, vcc
	v_cmp_class_f32_e32 vcc, v12, v105
	v_div_scale_f32 v24, s[2:3], 1.0, v8, 1.0
	v_fma_f32 v20, -v20, v26, v22
	v_fmac_f32_e32 v50, v46, v50
	v_cndmask_b32_e32 v12, v16, v12, vcc
	s_mov_b64 vcc, s[8:9]
	v_div_fmas_f32 v16, v20, v28, v26
	v_mul_f32_e32 v20, v24, v50
	v_div_scale_f32 v22, s[4:5], v12, v12, 1.0
	v_div_fixup_f32 v26, v16, v14, 1.0
	v_fma_f32 v14, -v18, v20, v24
	v_fma_f32 v16, -v27, v48, 1.0
	v_rcp_f32_e32 v46, v22
	v_div_scale_f32 v30, s[6:7], 1.0, v10, 1.0
	v_fmac_f32_e32 v20, v14, v50
	v_fmac_f32_e32 v48, v16, v48
	v_fma_f32 v14, -v18, v20, v24
	v_mul_f32_e32 v16, v30, v48
	s_mov_b64 vcc, s[2:3]
	v_div_fmas_f32 v14, v14, v50, v20
	v_fma_f32 v18, -v27, v16, v30
	v_mov_b32_e32 v88, v54
	v_div_fixup_f32 v54, v14, v8, 1.0
	v_fmac_f32_e32 v16, v18, v48
	v_fma_f32 v8, -v22, v46, 1.0
	v_mov_b32_e32 v90, v56
	v_div_scale_f32 v28, s[4:5], 1.0, v12, 1.0
	v_fma_f32 v14, -v27, v16, v30
	v_fmac_f32_e32 v46, v8, v46
	s_mov_b64 vcc, s[6:7]
	v_mov_b32_e32 v92, v58
	v_mov_b32_e32 v94, v60
	v_pk_mul_f32 v[88:89], v[26:27], v[88:89] op_sel_hi:[0,1]
	v_pk_mul_f32 v[90:91], v[26:27], v[90:91] op_sel_hi:[0,1]
	v_div_fmas_f32 v8, v14, v48, v16
	v_mul_f32_e32 v14, v28, v46
	v_mov_b32_e32 v96, v64
	v_mov_b32_e32 v97, v62
	v_mov_b32_e32 v98, v66
	v_pk_mul_f32 v[92:93], v[26:27], v[92:93] op_sel_hi:[0,1]
	v_pk_mul_f32 v[94:95], v[26:27], v[94:95] op_sel_hi:[0,1]
	v_pk_mul_f32 v[90:91], v[6:7], v[90:91]
	v_pk_mul_f32 v[88:89], v[4:5], v[88:89]
	v_div_fixup_f32 v56, v8, v10, 1.0
	v_fma_f32 v8, -v22, v14, v28
	v_mov_b32_e32 v100, v68
	v_mov_b32_e32 v102, v70
	v_pk_mul_f32 v[94:95], v[2:3], v[94:95]
	v_pk_mul_f32 v[92:93], v[0:1], v[92:93]
	global_store_dwordx4 v[36:37], v[88:91], off nt
	global_store_dwordx4 v[36:37], v[92:95], off offset:16 nt
	v_fmac_f32_e32 v14, v8, v46
	v_pk_mul_f32 v[88:89], v[54:55], v[96:97] op_sel_hi:[0,1]
	v_pk_mul_f32 v[90:91], v[54:55], v[98:99] op_sel_hi:[0,1]
	v_mov_b32_e32 v106, v72
	v_mov_b32_e32 v108, v74
	v_pk_mul_f32 v[92:93], v[54:55], v[100:101] op_sel_hi:[0,1]
	v_pk_mul_f32 v[94:95], v[54:55], v[102:103] op_sel_hi:[0,1]
	v_pk_mul_f32 v[90:91], v[6:7], v[90:91]
	v_pk_mul_f32 v[88:89], v[4:5], v[88:89]
	v_fma_f32 v8, -v22, v14, v28
	s_mov_b64 vcc, s[4:5]
	v_mov_b32_e32 v110, v76
	v_mov_b32_e32 v112, v78
	v_pk_mul_f32 v[94:95], v[2:3], v[94:95]
	v_pk_mul_f32 v[92:93], v[0:1], v[92:93]
	global_store_dwordx4 v[38:39], v[88:91], off nt
	global_store_dwordx4 v[38:39], v[92:95], off offset:16 nt
	v_div_fmas_f32 v8, v8, v46, v14
	v_pk_mul_f32 v[88:89], v[56:57], v[106:107] op_sel_hi:[0,1]
	v_pk_mul_f32 v[90:91], v[56:57], v[108:109] op_sel_hi:[0,1]
	v_mov_b32_e32 v120, v80
	v_mov_b32_e32 v122, v82
	v_pk_mul_f32 v[92:93], v[56:57], v[110:111] op_sel_hi:[0,1]
	v_pk_mul_f32 v[94:95], v[56:57], v[112:113] op_sel_hi:[0,1]
	v_pk_mul_f32 v[90:91], v[6:7], v[90:91]
	v_pk_mul_f32 v[88:89], v[4:5], v[88:89]
	v_div_fixup_f32 v58, v8, v12, 1.0
	v_mov_b32_e32 v124, v84
	v_mov_b32_e32 v126, v86
	v_pk_mul_f32 v[94:95], v[2:3], v[94:95]
	v_pk_mul_f32 v[92:93], v[0:1], v[92:93]
	global_store_dwordx4 v[42:43], v[88:91], off nt
	global_store_dwordx4 v[42:43], v[92:95], off offset:16 nt
	v_mov_b32_e32 v48, v57
	v_pk_mul_f32 v[88:89], v[58:59], v[120:121] op_sel_hi:[0,1]
	v_pk_mul_f32 v[90:91], v[58:59], v[122:123] op_sel_hi:[0,1]
	v_pk_mul_f32 v[92:93], v[58:59], v[124:125] op_sel_hi:[0,1]
	v_pk_mul_f32 v[94:95], v[58:59], v[126:127] op_sel_hi:[0,1]
	v_pk_mul_f32 v[6:7], v[6:7], v[90:91]
	v_pk_mul_f32 v[4:5], v[4:5], v[88:89]
	v_pk_mul_f32 v[2:3], v[2:3], v[94:95]
	v_pk_mul_f32 v[0:1], v[0:1], v[92:93]
	global_store_dwordx4 v[44:45], v[4:7], off nt
	global_store_dwordx4 v[44:45], v[0:3], off offset:16 nt
	global_load_dwordx4 v[0:3], v[40:41], off offset:2048
	s_nop 0
	global_load_dwordx4 v[4:7], v[40:41], off offset:2064
	v_mov_b32_e32 v46, v55
	v_mov_b32_e32 v52, v61
	v_mov_b32_e32 v50, v59
	v_mov_b32_e32 v20, v67
	v_mov_b32_e32 v62, v65
	v_mov_b32_e32 v22, v71
	v_mov_b32_e32 v16, v69
	v_mov_b32_e32 v12, v75
	v_mov_b32_e32 v18, v73
	v_mov_b32_e32 v14, v79
	v_mov_b32_e32 v8, v77
	v_mov_b32_e32 v28, v83
	v_mov_b32_e32 v10, v81
	v_mov_b32_e32 v30, v87
	v_mov_b32_e32 v24, v85
	v_pk_mul_f32 v[40:41], v[26:27], v[48:49] op_sel_hi:[0,1]
	v_pk_mul_f32 v[46:47], v[26:27], v[46:47] op_sel_hi:[0,1]
	v_pk_mul_f32 v[48:49], v[26:27], v[52:53] op_sel_hi:[0,1]
	v_pk_mul_f32 v[26:27], v[26:27], v[50:51] op_sel_hi:[0,1]
	v_pk_mul_f32 v[20:21], v[54:55], v[20:21] op_sel_hi:[0,1]
	v_pk_mul_f32 v[50:51], v[54:55], v[62:63] op_sel_hi:[0,1]
	v_pk_mul_f32 v[22:23], v[54:55], v[22:23] op_sel_hi:[0,1]
	v_pk_mul_f32 v[52:53], v[54:55], v[16:17] op_sel_hi:[0,1]
	v_pk_mul_f32 v[54:55], v[56:57], v[12:13] op_sel_hi:[0,1]
	v_pk_mul_f32 v[60:61], v[56:57], v[18:19] op_sel_hi:[0,1]
	v_pk_mul_f32 v[62:63], v[56:57], v[14:15] op_sel_hi:[0,1]
	v_pk_mul_f32 v[56:57], v[56:57], v[8:9] op_sel_hi:[0,1]
	v_pk_mul_f32 v[64:65], v[58:59], v[28:29] op_sel_hi:[0,1]
	v_pk_mul_f32 v[66:67], v[58:59], v[10:11] op_sel_hi:[0,1]
	v_pk_mul_f32 v[68:69], v[58:59], v[30:31] op_sel_hi:[0,1]
	v_pk_mul_f32 v[58:59], v[58:59], v[24:25] op_sel_hi:[0,1]
	s_waitcnt vmcnt(1)
	v_pk_mul_f32 v[8:9], v[46:47], v[0:1]
	v_pk_mul_f32 v[10:11], v[40:41], v[2:3]
	s_waitcnt vmcnt(0)
	v_pk_mul_f32 v[12:13], v[26:27], v[4:5]
	v_pk_mul_f32 v[14:15], v[48:49], v[6:7]
	v_pk_mul_f32 v[16:17], v[50:51], v[0:1]
	v_pk_mul_f32 v[18:19], v[20:21], v[2:3]
	v_pk_mul_f32 v[20:21], v[52:53], v[4:5]
	v_pk_mul_f32 v[22:23], v[22:23], v[6:7]
	v_pk_mul_f32 v[24:25], v[60:61], v[0:1]
	v_pk_mul_f32 v[26:27], v[54:55], v[2:3]
	v_pk_mul_f32 v[28:29], v[56:57], v[4:5]
	v_pk_mul_f32 v[30:31], v[62:63], v[6:7]
	v_pk_mul_f32 v[0:1], v[66:67], v[0:1]
	v_pk_mul_f32 v[2:3], v[64:65], v[2:3]
	v_pk_mul_f32 v[4:5], v[58:59], v[4:5]
	v_pk_mul_f32 v[6:7], v[68:69], v[6:7]
	global_store_dwordx4 v[36:37], v[8:11], off offset:2048 nt
	global_store_dwordx4 v[36:37], v[12:15], off offset:2064 nt
	global_store_dwordx4 v[38:39], v[16:19], off offset:2048 nt
	global_store_dwordx4 v[38:39], v[20:23], off offset:2064 nt
	global_store_dwordx4 v[42:43], v[24:27], off offset:2048 nt
	global_store_dwordx4 v[42:43], v[28:31], off offset:2064 nt
	global_store_dwordx4 v[44:45], v[0:3], off offset:2048 nt
	global_store_dwordx4 v[44:45], v[4:7], off offset:2064 nt
	s_cbranch_scc0 .LBB0_788
	s_endpgm
